# dil/NSA q-fragment loads issued together, compress W2 GEMM loads batched, barrier census loads de-serialised
# baseline (speedup 1.0000x reference)
; __device__ __forceinline__ unsigned xb_ld(unsigned* p)              { return __hip_atomic_load(p, __ATOMIC_RELAXED, __HIP_MEMORY_SCOPE_AGENT); }
; __device__ __forceinline__ void xcd_barrier_complete(unsigned* bar, unsigned x, unsigned& nloc, unsigned& nx) {
;     const unsigned G = gridDim.x * gridDim.y * gridDim.z;
;     unsigned sum, cnt, mine, sp = 0u;
;     for (;;) {
;         sum = 0u; cnt = 0u; mine = 0u;
; #pragma unroll
;         for (unsigned j = 0; j < 16; ++j) { const unsigned c = xb_ld(&bar[XB_XCNT(j)]); sum += c; cnt += (c > 0u) ? 1u : 0u; mine = (j == x) ? c : mine; }
;         if (sum == G) break;
;         __builtin_amdgcn_s_sleep(1);
;         if ((++sp & 255u) == 0u) { if (xb_ld(&bar[XB_TMO])) break; if (sp > XB_SPIN_CAP) { atomicAdd(&bar[XB_TMO], 1u); break; } }
;     }
;     nloc = mine > 0u ? mine : 1u; nx = cnt > 0u ? cnt : 1u;
; }
.LBB0_678:
	v_readlane_b32 s4, v252, 30
	v_readlane_b32 s5, v252, 31
	v_readlane_b32 s6, v253, 27
	s_nop 3
	global_load_dword v0, v1, s[4:5] sc1
	v_readlane_b32 s4, v252, 32
	v_readlane_b32 s5, v252, 33
	s_waitcnt lgkmcnt(0)
	s_nop 3
	global_load_dword v2, v1, s[4:5] sc1
	v_readlane_b32 s4, v252, 34
	v_readlane_b32 s5, v252, 35
	s_nop 4
	global_load_dword v3, v1, s[4:5] sc1
	v_readlane_b32 s4, v252, 36
	v_readlane_b32 s5, v252, 37
	s_nop 4
	global_load_dword v4, v1, s[4:5] sc1
	v_readlane_b32 s4, v252, 38
	v_readlane_b32 s5, v252, 39
	s_nop 4
	global_load_dword v5, v1, s[4:5] sc1
	v_readlane_b32 s4, v252, 40
	v_readlane_b32 s5, v252, 41
	s_nop 4
	global_load_dword v6, v1, s[4:5] sc1
	v_readlane_b32 s4, v252, 42
	v_readlane_b32 s5, v252, 43
	s_nop 4
	global_load_dword v7, v1, s[4:5] sc1
	v_readlane_b32 s4, v252, 44
	v_readlane_b32 s5, v252, 45
	s_nop 4
	global_load_dword v8, v1, s[4:5] sc1
	v_readlane_b32 s4, v252, 46
	v_readlane_b32 s5, v252, 47
	s_nop 4
	global_load_dword v9, v1, s[4:5] sc1
	v_readlane_b32 s4, v252, 48
	v_readlane_b32 s5, v252, 49
	s_nop 4
	global_load_dword v10, v1, s[4:5] sc1
	v_readlane_b32 s4, v252, 50
	v_readlane_b32 s5, v252, 51
	s_nop 4
	global_load_dword v11, v1, s[4:5] sc1
	v_readlane_b32 s4, v252, 52
	v_readlane_b32 s5, v252, 53
	s_nop 4
	global_load_dword v12, v1, s[4:5] sc1
	v_readlane_b32 s4, v252, 54
	v_readlane_b32 s5, v252, 55
	s_nop 4
	global_load_dword v13, v1, s[4:5] sc1
	v_readlane_b32 s4, v252, 56
	v_readlane_b32 s5, v252, 57
	s_nop 4
	global_load_dword v14, v1, s[4:5] sc1
	v_readlane_b32 s4, v252, 58
	v_readlane_b32 s5, v252, 59
	s_nop 4
	global_load_dword v15, v1, s[4:5] sc1
	v_readlane_b32 s4, v252, 60
	v_readlane_b32 s5, v252, 61
	s_nop 4
	global_load_dword v16, v1, s[4:5] sc1
	s_mov_b64 s[4:5], -1
	s_waitcnt vmcnt(0)
	v_add_u32_e32 v17, v2, v0
	v_add_u32_e32 v17, v17, v3
	v_add_u32_e32 v17, v17, v4
	v_add_u32_e32 v17, v17, v5
	v_add_u32_e32 v17, v17, v6
	v_add_u32_e32 v17, v17, v7
	v_add_u32_e32 v17, v17, v8
	v_add_u32_e32 v17, v17, v9
	v_add_u32_e32 v17, v17, v10
	v_add_u32_e32 v17, v17, v11
	v_add_u32_e32 v17, v17, v12
	v_add_u32_e32 v17, v17, v13
	v_add_u32_e32 v17, v17, v14
	v_add_u32_e32 v17, v17, v15
	v_add_u32_e32 v17, v17, v16
	v_cmp_eq_u32_e32 vcc, s6, v17
	s_mov_b64 s[6:7], -1
	s_cbranch_vccnz .LBB0_677
	s_and_b32 s4, s12, 0xff
	s_cmp_eq_u32 s4, 0
	s_mov_b64 s[4:5], -1
	s_mov_b64 s[8:9], -1
	s_sleep 1
	s_cbranch_scc1 .LBB0_682
	s_and_b64 vcc, exec, s[8:9]
	s_cbranch_vccz .LBB0_677

; #define LAS __attribute__((address_space(3)))
; __device__ __forceinline__ float sum32(float v) { auto rr = __builtin_amdgcn_permlane32_swap(__float_as_uint(v), __float_as_uint(v), false, false); return __uint_as_float(rr[0]) + __uint_as_float(rr[1]); }
; #define UNPACK8(v, k) const float k##0 = blo(v.x), k##1 = bhi(v.x), k##2 = blo(v.y), k##3 = bhi(v.y), k##4 = blo(v.z), k##5 = bhi(v.z), k##6 = blo(v.w), k##7 = bhi(v.w)
; template <bool NORM> __device__ __forceinline__ void load_qfrag(bf16x8 (&qf)[4], const bf16_t* qrow, const float* g1, const float* g2, float sc, int hh) {
;     float f[32];
; #pragma unroll
;     for (int s = 0; s < 4; ++s) { const u32x4 v = *(const u32x4*)(qrow + 16 * s + 8 * hh); UNPACK8(v, k);
;         f[8 * s] = k0; f[8 * s + 1] = k1; f[8 * s + 2] = k2; f[8 * s + 3] = k3; f[8 * s + 4] = k4; f[8 * s + 5] = k5; f[8 * s + 6] = k6; f[8 * s + 7] = k7; }
;     if (NORM) { float ss = 0.f;
; #pragma unroll
;         for (int i = 0; i < 32; ++i) ss += f[i] * f[i];
;         ss = sum32(ss); sc *= rsqrtf(ss * (1.f / 64.f) + EPS); }
; __device__ __forceinline__ void dil_item(const DilArgs& A, int item, LAS unsigned char* lds, int tid) {
;     asm volatile("" : "+v"(tid));
;     const int cfg = item >> 9, rem = item & 511, b = rem >> 6, head = (rem >> 4) & 3, sub = rem & 15;
;     const int dil = cfg == 0 ? 1 : (cfg == 1 ? 4 : 16), nq = 16 / dil, c = sub / nq, qt = sub % nq, i0 = 256 * qt, L = SEQ / dil;
;     const int lane = tid & 63, w = __builtin_amdgcn_readfirstlane(tid >> 6), r = lane & 31, hh = lane >> 5;
;     const int iq = i0 + 32 * w + r, tq = c + dil * iq; const size_t token = (size_t)b * SEQ + tq;
;     const bf16_t* base = A.proj + (size_t)b * SEQ * NP;
;     const float slope = exp2f(-(float)(2 * head + 2)) * (float)dil * LOG2E;
;     bf16x8 qf[4]; load_qfrag<true>(qf, base + (size_t)tq * NP + C_QD + head * 64, A.g_q, nullptr, 0.125f * LOG2E, hh);
.LBB0_776:
	s_andn2_b64 vcc, exec, s[0:1]
	s_cbranch_vccnz .LBB0_878
	s_add_i32 s4, s14, 0xfffffd80
	s_lshr_b32 s40, s4, 9
	s_bfe_u32 s15, s14, 0x20004
	s_and_b32 s5, s14, 15
	s_cmp_eq_u32 s40, 1
	s_cselect_b64 s[6:7], -1, 0
	s_and_b64 s[0:1], s[6:7], exec
	s_cselect_b32 s12, 2, 4
	s_cmpk_lt_u32 s4, 0x200
	s_cselect_b64 s[8:9], -1, 0
	s_and_b64 s[0:1], s[8:9], exec
	s_cselect_b32 s24, 0, s12
	v_mov_b32_e32 v30, v125
	s_lshr_b32 s0, 16, s24
	s_sub_i32 s1, 4, s24
	s_lshr_b32 s25, s5, s1
	s_add_i32 s0, s0, -1
	v_readfirstlane_b32 s1, v30
	s_and_b32 s13, s0, s5
	s_ashr_i32 s1, s1, 1
	s_lshl_b32 s0, s13, 8
	s_and_b32 s42, s1, 0xffffffe0
	s_add_i32 s42, s42, s0
	s_lshl_b32 s0, s4, 6
	s_and_b32 s41, s0, 0x7000
	v_and_b32_e32 v21, 31, v30
	s_mul_i32 s0, s41, 0x1800
	v_or_b32_e32 v0, s42, v21
	s_add_u32 s16, s68, s0
	v_lshlrev_b32_e32 v0, s24, v0
	s_addc_u32 s17, s69, 0
	v_add_u32_e32 v94, s25, v0
	v_mov_b64_e32 v[2:3], s[16:17]
	v_bfe_u32 v106, v30, 5, 1
	v_mad_i64_i32 v[2:3], s[0:1], v94, s39, v[2:3]
	s_lshl_b32 s30, s15, 7
	v_lshl_add_u64 v[2:3], v[2:3], 0, s[30:31]
	v_lshlrev_b32_e32 v0, 4, v106
	v_lshl_add_u64 v[2:3], v[2:3], 0, v[0:1]
	s_mov_b64 s[0:1], 0x1100
	v_lshl_add_u64 v[6:7], v[2:3], 0, s[0:1]
	v_add_co_u32_e32 v2, vcc, s72, v2
	v_readlane_b32 s4, v254, 40
	s_nop 0
	v_addc_co_u32_e32 v3, vcc, 0, v3, vcc
	global_load_dwordx4 v[2:5], v[2:3], off offset:256
	global_load_dwordx4 v[22:25], v[6:7], off offset:32
	global_load_dwordx4 v[26:29], v[6:7], off offset:64
	global_load_dwordx4 v[96:99], v[6:7], off offset:96
	v_readlane_b32 s5, v254, 41
	v_lshlrev_b32_e32 v92, 3, v106
	s_andn2_b64 vcc, exec, s[4:5]
	v_mov_b32_e32 v55, 1.0
	v_mov_b32_e32 v56, 1.0
	s_waitcnt vmcnt(3)
	v_lshlrev_b32_e32 v32, 16, v2
	v_and_b32_e32 v31, 0xffff0000, v2
	v_lshlrev_b32_e32 v34, 16, v3
	v_and_b32_e32 v33, 0xffff0000, v3
	v_lshlrev_b32_e32 v36, 16, v4
	v_and_b32_e32 v35, 0xffff0000, v4
	v_lshlrev_b32_e32 v38, 16, v5
	v_and_b32_e32 v37, 0xffff0000, v5
	s_waitcnt vmcnt(2)
	v_lshlrev_b32_e32 v40, 16, v22
	v_and_b32_e32 v39, 0xffff0000, v22
	v_lshlrev_b32_e32 v42, 16, v23
	v_and_b32_e32 v41, 0xffff0000, v23
	v_lshlrev_b32_e32 v44, 16, v24
	v_and_b32_e32 v43, 0xffff0000, v24
	v_lshlrev_b32_e32 v46, 16, v25
	v_and_b32_e32 v45, 0xffff0000, v25
	s_waitcnt vmcnt(1)
	v_lshlrev_b32_e32 v48, 16, v26
	v_and_b32_e32 v47, 0xffff0000, v26
	v_lshlrev_b32_e32 v50, 16, v27
	v_and_b32_e32 v49, 0xffff0000, v27
	v_lshlrev_b32_e32 v52, 16, v28
	v_and_b32_e32 v51, 0xffff0000, v28
	v_lshlrev_b32_e32 v54, 16, v29
	v_and_b32_e32 v53, 0xffff0000, v29
	s_waitcnt vmcnt(0)
	v_lshlrev_b32_e32 v10, 16, v98
	v_and_b32_e32 v11, 0xffff0000, v98
	v_mul_f32_e32 v4, v31, v31
	v_fmac_f32_e32 v4, v32, v32
	v_fmac_f32_e32 v4, v34, v34
	v_fmac_f32_e32 v4, v33, v33
	v_fmac_f32_e32 v4, v36, v36
	v_fmac_f32_e32 v4, v35, v35
	v_fmac_f32_e32 v4, v38, v38
	v_fmac_f32_e32 v4, v37, v37
	v_fmac_f32_e32 v4, v40, v40
	v_fmac_f32_e32 v4, v39, v39
	v_fmac_f32_e32 v4, v42, v42
	v_fmac_f32_e32 v4, v41, v41
	v_fmac_f32_e32 v4, v44, v44
	v_fmac_f32_e32 v4, v43, v43
	v_fmac_f32_e32 v4, v46, v46
	v_fmac_f32_e32 v4, v45, v45
	v_fmac_f32_e32 v4, v48, v48
	v_fmac_f32_e32 v4, v47, v47
	v_fmac_f32_e32 v4, v50, v50
	v_fmac_f32_e32 v4, v49, v49
	v_fmac_f32_e32 v4, v52, v52
	v_fmac_f32_e32 v4, v51, v51
	v_lshlrev_b32_e32 v16, 16, v96
	v_and_b32_e32 v17, 0xffff0000, v96
	v_fmac_f32_e32 v4, v54, v54
	v_lshlrev_b32_e32 v12, 16, v97
	v_and_b32_e32 v13, 0xffff0000, v97
	v_fmac_f32_e32 v4, v53, v53
	v_pk_mul_f32 v[2:3], v[16:17], v[16:17]
	v_lshlrev_b32_e32 v18, 16, v99
	v_add_f32_e32 v2, v2, v4
	v_add_f32_e32 v4, v3, v2
	v_pk_mul_f32 v[2:3], v[12:13], v[12:13]
	v_and_b32_e32 v19, 0xffff0000, v99
	v_add_f32_e32 v2, v2, v4
	v_add_f32_e32 v4, v3, v2
	v_pk_mul_f32 v[2:3], v[10:11], v[10:11]
	s_nop 0
	v_add_f32_e32 v2, v2, v4
	v_add_f32_e32 v4, v3, v2
	v_pk_mul_f32 v[2:3], v[18:19], v[18:19]
	s_nop 0
	v_add_f32_e32 v2, v2, v4
	v_add_f32_e32 v2, v3, v2
	v_mov_b32_e32 v3, v2
	v_cndmask_b32_e64 v4, 0, 1, s[4:5]
	v_readlane_b32 s4, v255, 4
	v_permlane32_swap_b32_e32 v2, v3
	v_cmp_ne_u32_e64 s[0:1], 1, v4
	v_lshlrev_b32_e32 v4, 2, v92
	v_readlane_b32 s5, v255, 5
	s_cbranch_vccnz .LBB0_779
	s_nop 3
	global_load_dword v56, v4, s[4:5]

; #define LAS __attribute__((address_space(3)))
; __device__ __forceinline__ unsigned cvtpk(float lo, float hi) { f32x2_t v = {lo, hi}; bf16x2_t b = __builtin_convertvector(v, bf16x2_t); return __builtin_bit_cast(unsigned, b); }
; #define MFMA32(a, b, c) __builtin_amdgcn_mfma_f32_32x32x16_bf16((a), (b), (c), 0, 0, 0)
; __device__ __forceinline__ int crow(int i, int h) { return (i & 3) + 8 * (i >> 2) + 4 * h; }
; __device__ __forceinline__ void compress_item(const CmpArgs& A, int item, LAS unsigned char* lds, int tid) {
;     ...
;       for (int i = 0; i < 16; ++i) { const float x = acc[i] + bias; const float hv = 0.5f * x * (1.f + tanhf(0.7978845608028654f * (x + 0.044715f * x * x * x)));
;           *(LAS unsigned short*)(lds + crow(i, hh) * HIDB + (32 * w + r) * 2) = (unsigned short)(cvtpk(hv, hv) & 0xffffu); } }
;     __syncthreads();
;     if (w == 0) {
;         f32x16 c0, c1;
; #pragma unroll
;         for (int i = 0; i < 16; ++i) { c0[i] = 0.f; c1[i] = 0.f; }
;         const bf16_t* w2a = A.w2t + ((size_t)kv * 64 + r) * 256 + 8 * hh; const bf16_t* w2b = w2a + 32 * 256;
; #pragma unroll
;         for (int s = 0; s < 16; ++s) { const bf16x8 af = *(LAS const bf16x8*)(lds + r * HIDB + (16 * s + 8 * hh) * 2);
;             c0 = MFMA32(af, *(const bf16x8*)(w2a + 16 * s), c0); c1 = MFMA32(af, *(const bf16x8*)(w2b + 16 * s), c1); }
.LBB0_993:
	s_andn2_saveexec_b64 s[8:9], s[8:9]
	v_mul_f32_e32 v4, v3, v3
	v_fmamk_f32 v5, v4, 0xbbbac73d, v209
	v_fmaak_f32 v5, v4, v5, 0xbd5c1c4e
	v_fmaak_f32 v5, v4, v5, 0x3e088382
	v_fmaak_f32 v5, v4, v5, 0xbeaaaa99
	v_mul_f32_e64 v5, |v3|, v5
	v_fma_f32 v4, v4, v5, |v3|
	s_or_b64 exec, exec, s[8:9]
	v_bfi_b32 v3, s75, v4, v3
	v_mul_f32_e32 v0, 0.5, v0
	v_add_f32_e32 v3, 1.0, v3
	v_mul_f32_e32 v0, v0, v3
	v_cvt_pk_bf16_f32 v0, v0, s0
	s_cmp_lt_u32 s26, 64
	ds_write_b16 v2, v0 offset:13728
	s_waitcnt lgkmcnt(0)
	s_barrier
	s_cbranch_scc0 .LBB0_728
	s_lshl_b64 s[0:1], s[0:1], 15
	v_readlane_b32 s8, v253, 62
	s_add_u32 s0, s8, s0
	v_readlane_b32 s8, v253, 63
	s_addc_u32 s1, s8, s1
	v_lshlrev_b32_e32 v0, 9, v38
	v_lshl_add_u64 v[2:3], s[0:1], 0, v[0:1]
	v_mov_b32_e32 v19, v1
	v_lshl_add_u64 v[34:35], v[2:3], 0, v[18:19]
	s_movk_i32 s0, 0x4000
	v_mul_u32_u24_e32 v0, 0x210, v38
	v_add_co_u32_e32 v36, vcc, s0, v34
	v_add3_u32 v0, 0, v0, v18
	s_nop 0
	v_addc_co_u32_e32 v37, vcc, 0, v35, vcc
	v_mov_b64_e32 v[114:115], v[34:35]
	v_mov_b64_e32 v[116:117], v[36:37]
	global_load_dwordx4 v[50:53], v[114:115], off
	global_load_dwordx4 v[54:57], v[116:117], off
	global_load_dwordx4 v[58:61], v[114:115], off offset:32
	global_load_dwordx4 v[62:65], v[116:117], off offset:32
	global_load_dwordx4 v[66:69], v[114:115], off offset:64
	global_load_dwordx4 v[70:73], v[116:117], off offset:64
	global_load_dwordx4 v[74:77], v[114:115], off offset:96
	global_load_dwordx4 v[78:81], v[116:117], off offset:96
	global_load_dwordx4 v[82:85], v[114:115], off offset:128
	global_load_dwordx4 v[86:89], v[116:117], off offset:128
	global_load_dwordx4 v[90:93], v[114:115], off offset:160
	global_load_dwordx4 v[94:97], v[116:117], off offset:160
	global_load_dwordx4 v[98:101], v[114:115], off offset:192
	global_load_dwordx4 v[102:105], v[116:117], off offset:192
	global_load_dwordx4 v[106:109], v[114:115], off offset:224
	global_load_dwordx4 v[110:113], v[116:117], off offset:224
	v_readlane_b32 s0, v255, 2
	v_readlane_b32 s1, v255, 3
	s_and_b64 vcc, s[6:7], exec
	ds_read_b128 v[42:45], v0
	ds_read_b128 v[46:49], v0 offset:32
	s_waitcnt vmcnt(14) lgkmcnt(1)
	v_mfma_f32_32x32x16_bf16 v[2:17], v[42:45], v[50:53], 0
	v_mfma_f32_32x32x16_bf16 v[18:33], v[42:45], v[54:57], 0
	ds_read_b128 v[42:45], v0 offset:64
	s_waitcnt vmcnt(12) lgkmcnt(1)
	v_mfma_f32_32x32x16_bf16 v[2:17], v[46:49], v[58:61], v[2:17]
	v_mfma_f32_32x32x16_bf16 v[18:33], v[46:49], v[62:65], v[18:33]
	ds_read_b128 v[46:49], v0 offset:96
	s_waitcnt vmcnt(10) lgkmcnt(1)
	v_mfma_f32_32x32x16_bf16 v[2:17], v[42:45], v[66:69], v[2:17]
	v_mfma_f32_32x32x16_bf16 v[18:33], v[42:45], v[70:73], v[18:33]
	ds_read_b128 v[42:45], v0 offset:128
	s_waitcnt vmcnt(8) lgkmcnt(1)
	v_mfma_f32_32x32x16_bf16 v[2:17], v[46:49], v[74:77], v[2:17]
	v_mfma_f32_32x32x16_bf16 v[18:33], v[46:49], v[78:81], v[18:33]
	ds_read_b128 v[46:49], v0 offset:160
	s_waitcnt vmcnt(6) lgkmcnt(1)
	v_mfma_f32_32x32x16_bf16 v[2:17], v[42:45], v[82:85], v[2:17]
	v_mfma_f32_32x32x16_bf16 v[18:33], v[42:45], v[86:89], v[18:33]
	ds_read_b128 v[42:45], v0 offset:192
	s_waitcnt vmcnt(4) lgkmcnt(1)
	v_mfma_f32_32x32x16_bf16 v[2:17], v[46:49], v[90:93], v[2:17]
	v_mfma_f32_32x32x16_bf16 v[18:33], v[46:49], v[94:97], v[18:33]
	ds_read_b128 v[46:49], v0 offset:224
	s_waitcnt vmcnt(2) lgkmcnt(1)
	v_mfma_f32_32x32x16_bf16 v[2:17], v[42:45], v[98:101], v[2:17]
	v_mfma_f32_32x32x16_bf16 v[18:33], v[42:45], v[102:105], v[18:33]
	ds_read_b128 v[42:45], v0 offset:256
	s_waitcnt vmcnt(0) lgkmcnt(1)
	v_mfma_f32_32x32x16_bf16 v[2:17], v[46:49], v[106:109], v[2:17]
	v_mfma_f32_32x32x16_bf16 v[18:33], v[46:49], v[110:113], v[18:33]
	v_lshlrev_b32_e32 v118, 2, v38
	s_nop 3
	global_load_dword v35, v118, s[0:1]
	global_load_dword v34, v118, s[0:1] offset:128
	global_load_dwordx4 v[50:53], v[114:115], off offset:256
	global_load_dwordx4 v[54:57], v[116:117], off offset:256
	global_load_dwordx4 v[58:61], v[114:115], off offset:288
	global_load_dwordx4 v[62:65], v[116:117], off offset:288
	global_load_dwordx4 v[66:69], v[114:115], off offset:320
	global_load_dwordx4 v[70:73], v[116:117], off offset:320
	global_load_dwordx4 v[74:77], v[114:115], off offset:352
	global_load_dwordx4 v[78:81], v[116:117], off offset:352
	global_load_dwordx4 v[82:85], v[114:115], off offset:384
	global_load_dwordx4 v[86:89], v[116:117], off offset:384
	global_load_dwordx4 v[90:93], v[114:115], off offset:416
	global_load_dwordx4 v[94:97], v[116:117], off offset:416
	global_load_dwordx4 v[98:101], v[114:115], off offset:448
	global_load_dwordx4 v[102:105], v[116:117], off offset:448
	global_load_dwordx4 v[106:109], v[114:115], off offset:480
	global_load_dwordx4 v[110:113], v[116:117], off offset:480
	ds_read_b128 v[46:49], v0 offset:288
	s_waitcnt vmcnt(14) lgkmcnt(1)
	v_mfma_f32_32x32x16_bf16 v[2:17], v[42:45], v[50:53], v[2:17]
	v_mfma_f32_32x32x16_bf16 v[18:33], v[42:45], v[54:57], v[18:33]
	ds_read_b128 v[42:45], v0 offset:320
	s_waitcnt vmcnt(12) lgkmcnt(1)
	v_mfma_f32_32x32x16_bf16 v[2:17], v[46:49], v[58:61], v[2:17]
	v_mfma_f32_32x32x16_bf16 v[18:33], v[46:49], v[62:65], v[18:33]
	ds_read_b128 v[46:49], v0 offset:352
	s_waitcnt vmcnt(10) lgkmcnt(1)
	v_mfma_f32_32x32x16_bf16 v[2:17], v[42:45], v[66:69], v[2:17]
	v_mfma_f32_32x32x16_bf16 v[18:33], v[42:45], v[70:73], v[18:33]
	ds_read_b128 v[42:45], v0 offset:384
	s_waitcnt vmcnt(8) lgkmcnt(1)
	v_mfma_f32_32x32x16_bf16 v[2:17], v[46:49], v[74:77], v[2:17]
	v_mfma_f32_32x32x16_bf16 v[18:33], v[46:49], v[78:81], v[18:33]
	ds_read_b128 v[46:49], v0 offset:416
	s_waitcnt vmcnt(6) lgkmcnt(1)
	v_mfma_f32_32x32x16_bf16 v[2:17], v[42:45], v[82:85], v[2:17]
	v_mfma_f32_32x32x16_bf16 v[18:33], v[42:45], v[86:89], v[18:33]
	ds_read_b128 v[42:45], v0 offset:448
	s_waitcnt vmcnt(4) lgkmcnt(1)
	v_mfma_f32_32x32x16_bf16 v[2:17], v[46:49], v[90:93], v[2:17]
	v_mfma_f32_32x32x16_bf16 v[18:33], v[46:49], v[94:97], v[18:33]
	ds_read_b128 v[46:49], v0 offset:480
	s_waitcnt vmcnt(2) lgkmcnt(1)
	v_mfma_f32_32x32x16_bf16 v[2:17], v[42:45], v[98:101], v[2:17]
	v_mfma_f32_32x32x16_bf16 v[18:33], v[42:45], v[102:105], v[18:33]
	s_waitcnt vmcnt(0) lgkmcnt(0)
	v_mfma_f32_32x32x16_bf16 v[18:33], v[46:49], v[110:113], v[18:33]
	v_mfma_f32_32x32x16_bf16 v[2:17], v[46:49], v[106:109], v[2:17]
	v_lshlrev_b32_e32 v0, 2, v38
	s_cbranch_vccz .LBB0_998
; template <int K> __device__ __forceinline__ float swz_f(float v) { return __uint_as_float(swz_u<K>(__float_as_uint(v))); }
; __device__ __forceinline__ void compress_item(const CmpArgs& A, int item, LAS unsigned char* lds, int tid) {
;     ...
;         const float g0 = A.g_kc[r], g1 = A.g_kc[32 + r]; bf16_t* dst = (kv ? A.vcc : A.kcn) + ((size_t)b * 256 + j0) * 64;
; #pragma unroll
;         for (int i = 0; i < 16; ++i) { float v0 = c0[i], v1 = c1[i];
;             if (!kv) { float ss = v0 * v0 + v1 * v1; ss += swz_f<1>(ss); ss += swz_f<2>(ss); ss += swz_f<4>(ss); ss += swz_f<8>(ss); ss += swz_f<16>(ss);
;                 const float rs = rsqrtf(ss * (1.f / 64.f) + EPS); v0 *= rs * g0; v1 *= rs * g1; }
	s_nop 10
	v_mov_b32_e32 v36, v2
	v_mov_b32_e32 v37, v18
	v_pk_mul_f32 v[36:37], v[36:37], v[36:37]
	s_nop 0
	v_add_f32_e32 v0, v36, v37
	ds_swizzle_b32 v36, v0 offset:swizzle(SWAP,1)
	v_mov_b32_e32 v37, v2
	s_waitcnt lgkmcnt(0)
	v_add_f32_e32 v0, v0, v36
	ds_swizzle_b32 v36, v0 offset:swizzle(SWAP,2)
	s_waitcnt lgkmcnt(0)
	v_add_f32_e32 v0, v0, v36
	ds_swizzle_b32 v36, v0 offset:swizzle(SWAP,4)
	s_waitcnt lgkmcnt(0)
	v_add_f32_e32 v0, v0, v36
	ds_swizzle_b32 v36, v0 offset:swizzle(SWAP,8)
	s_waitcnt lgkmcnt(0)
	v_add_f32_e32 v0, v0, v36
	ds_swizzle_b32 v36, v0 offset:swizzle(SWAP,16)
	s_waitcnt lgkmcnt(0)
	v_add_f32_e32 v0, v0, v36
	v_fmamk_f32 v0, v0, 0x3c800000, v139
	v_mul_f32_e32 v36, 0x4b800000, v0
	v_cmp_gt_f32_e32 vcc, s71, v0
	s_nop 1
	v_cndmask_b32_e32 v0, v0, v36, vcc
	v_rsq_f32_e32 v0, v0
	v_mov_b32_e32 v36, v18
	v_mul_f32_e32 v2, 0x45800000, v0
	v_cndmask_b32_e32 v0, v0, v2, vcc
	s_waitcnt vmcnt(0)
	v_pk_mul_f32 v[42:43], v[34:35], v[0:1] op_sel_hi:[1,0]
	s_nop 0
	v_pk_mul_f32 v[36:37], v[36:37], v[42:43]
	s_nop 0
	v_mov_b32_e32 v18, v36
	v_mov_b32_e32 v2, v37

; #define LAS __attribute__((address_space(3)))
; __device__ __forceinline__ float sum32(float v) { auto rr = __builtin_amdgcn_permlane32_swap(__float_as_uint(v), __float_as_uint(v), false, false); return __uint_as_float(rr[0]) + __uint_as_float(rr[1]); }
; #define UNPACK8(v, k) const float k##0 = blo(v.x), k##1 = bhi(v.x), k##2 = blo(v.y), k##3 = bhi(v.y), k##4 = blo(v.z), k##5 = bhi(v.z), k##6 = blo(v.w), k##7 = bhi(v.w)
; template <bool NORM> __device__ __forceinline__ void load_qfrag(bf16x8 (&qf)[4], const bf16_t* qrow, const float* g1, const float* g2, float sc, int hh) {
;     float f[32];
; #pragma unroll
;     for (int s = 0; s < 4; ++s) { const u32x4 v = *(const u32x4*)(qrow + 16 * s + 8 * hh); UNPACK8(v, k);
;         f[8 * s] = k0; f[8 * s + 1] = k1; f[8 * s + 2] = k2; f[8 * s + 3] = k3; f[8 * s + 4] = k4; f[8 * s + 5] = k5; f[8 * s + 6] = k6; f[8 * s + 7] = k7; }
;     if (NORM) { float ss = 0.f;
; #pragma unroll
;         for (int i = 0; i < 32; ++i) ss += f[i] * f[i];
;         ss = sum32(ss); sc *= rsqrtf(ss * (1.f / 64.f) + EPS); }
; __device__ __forceinline__ void nsa_item(const NsaArgs& A, int b, int tl, LAS unsigned char* lds, int tid) {
;     asm volatile("" : "+v"(tid));
;     const int lane = tid & 63, w = __builtin_amdgcn_readfirstlane(tid >> 6), head = w & 3, half = w >> 2, r = lane & 31, hh = lane >> 5;
;     const int tq = tl * 64 + 32 * half + r, tokl = 32 * half + r; const size_t token = (size_t)b * SEQ + tq;
;     const bf16_t* base = A.proj + (size_t)b * SEQ * NP;
;     LAS float* slab = (LAS float*)(lds + NSA_SLAB); LAS float* isum = (LAS float*)(lds + NSA_ISUM);
;     LAS unsigned* masks = (LAS unsigned*)(lds + NSA_MASK); LAS unsigned* umask = (LAS unsigned*)(lds + NSA_UMASK);
;     const float slope = exp2f(-(float)(2 * head + 1)) * LOG2E;
;     bf16x8 qf[4]; load_qfrag<true>(qf, base + (size_t)tq * NP + C_QA + head * 64, A.g_q, nullptr, 0.125f * LOG2E, hh);
.LBB0_1163:
	s_andn2_b64 vcc, exec, s[0:1]
	s_cbranch_vccnz .LBB0_1154
	v_mov_b32_e32 v109, v93
	s_ashr_i32 s42, s27, 3
	s_sub_i32 s19, 63, s42
	v_readfirstlane_b32 s0, v109
	s_ashr_i32 s43, s0, 3
	s_lshl_b32 s1, s19, 6
	s_andn2_b32 s43, s43, 31
	s_and_b32 s18, s27, 7
	s_ashr_i32 s44, s0, 6
	v_and_b32_e32 v134, 31, v109
	s_add_i32 s0, s43, s1
	s_and_b32 s4, s44, 3
	v_or_b32_e32 v102, s0, v134
	s_mul_i32 s0, s18, 0x1800000
	s_add_u32 s0, s68, s0
	s_addc_u32 s1, s69, 0
	v_mov_b64_e32 v[2:3], s[0:1]
	v_bfe_u32 v20, v109, 5, 1
	v_mad_i64_i32 v[2:3], s[0:1], v102, s39, v[2:3]
	s_lshl_b32 s30, s4, 7
	v_lshl_add_u64 v[4:5], v[2:3], 0, s[30:31]
	v_lshlrev_b32_e32 v104, 4, v20
	v_mov_b32_e32 v105, v1
	v_lshl_add_u64 v[8:9], v[4:5], 0, v[104:105]
	global_load_dwordx4 v[4:7], v[8:9], off
	global_load_dwordx4 v[10:13], v[8:9], off offset:96
	global_load_dwordx4 v[72:75], v[8:9], off offset:32
	global_load_dwordx4 v[76:79], v[8:9], off offset:64
	v_readlane_b32 s6, v254, 60
	v_readlane_b32 s7, v254, 61
	v_lshlrev_b32_e32 v132, 3, v20
	v_mov_b32_e32 v46, 1.0
	s_andn2_b64 vcc, exec, s[6:7]
	v_lshlrev_b32_e32 v47, 2, v132
	v_mov_b32_e32 v48, 1.0
	s_waitcnt vmcnt(3)
	v_lshlrev_b32_e32 v22, 16, v4
	v_and_b32_e32 v21, 0xffff0000, v4
	v_lshlrev_b32_e32 v24, 16, v5
	v_and_b32_e32 v23, 0xffff0000, v5
	v_lshlrev_b32_e32 v26, 16, v6
	v_and_b32_e32 v25, 0xffff0000, v6
	v_lshlrev_b32_e32 v28, 16, v7
	v_and_b32_e32 v27, 0xffff0000, v7
	v_mul_f32_e32 v0, v21, v21
	v_fmac_f32_e32 v0, v22, v22
	v_fmac_f32_e32 v0, v24, v24
	v_fmac_f32_e32 v0, v23, v23
	v_fmac_f32_e32 v0, v26, v26
	v_fmac_f32_e32 v0, v25, v25
	v_fmac_f32_e32 v0, v28, v28
	v_fmac_f32_e32 v0, v27, v27
	s_waitcnt vmcnt(1)
	v_lshlrev_b32_e32 v30, 16, v72
	v_and_b32_e32 v29, 0xffff0000, v72
	v_lshlrev_b32_e32 v32, 16, v73
	v_and_b32_e32 v31, 0xffff0000, v73
	v_lshlrev_b32_e32 v34, 16, v74
	v_and_b32_e32 v33, 0xffff0000, v74
	v_lshlrev_b32_e32 v36, 16, v75
	v_and_b32_e32 v35, 0xffff0000, v75
	v_fmac_f32_e32 v0, v30, v30
	v_fmac_f32_e32 v0, v29, v29
	v_fmac_f32_e32 v0, v32, v32
	v_fmac_f32_e32 v0, v31, v31
	v_fmac_f32_e32 v0, v34, v34
	v_fmac_f32_e32 v0, v33, v33
	v_fmac_f32_e32 v0, v36, v36
	v_fmac_f32_e32 v0, v35, v35
	v_lshlrev_b32_e32 v8, 16, v10
	v_and_b32_e32 v9, 0xffff0000, v10
	v_lshlrev_b32_e32 v10, 16, v13
	s_waitcnt vmcnt(0)
	v_lshlrev_b32_e32 v38, 16, v76
	v_and_b32_e32 v37, 0xffff0000, v76
	v_fmac_f32_e32 v0, v38, v38
	v_lshlrev_b32_e32 v40, 16, v77
	v_fmac_f32_e32 v0, v37, v37
	v_and_b32_e32 v39, 0xffff0000, v77
	v_fmac_f32_e32 v0, v40, v40
	v_lshlrev_b32_e32 v42, 16, v78
	v_fmac_f32_e32 v0, v39, v39
	v_and_b32_e32 v41, 0xffff0000, v78
	v_fmac_f32_e32 v0, v42, v42
	v_lshlrev_b32_e32 v44, 16, v79
	v_fmac_f32_e32 v0, v41, v41
	v_and_b32_e32 v43, 0xffff0000, v79
	v_fmac_f32_e32 v0, v44, v44
	v_lshlrev_b32_e32 v6, 16, v11
	v_and_b32_e32 v7, 0xffff0000, v11
	v_lshlrev_b32_e32 v4, 16, v12
	v_and_b32_e32 v5, 0xffff0000, v12
	v_and_b32_e32 v11, 0xffff0000, v13
	v_fmac_f32_e32 v0, v43, v43
	v_pk_mul_f32 v[12:13], v[8:9], v[8:9]
	s_nop 0
	v_add_f32_e32 v0, v12, v0
	v_add_f32_e32 v0, v13, v0
	v_pk_mul_f32 v[12:13], v[6:7], v[6:7]
	s_nop 0
	v_add_f32_e32 v0, v12, v0
	v_add_f32_e32 v0, v13, v0
	v_pk_mul_f32 v[12:13], v[4:5], v[4:5]
	s_nop 0
	v_add_f32_e32 v0, v12, v0
	v_add_f32_e32 v0, v13, v0
	v_pk_mul_f32 v[12:13], v[10:11], v[10:11]
	s_nop 0
	v_add_f32_e32 v0, v12, v0
	v_add_f32_e32 v0, v13, v0
	v_mov_b32_e32 v45, v0
	v_cndmask_b32_e64 v12, 0, 1, s[6:7]
	s_nop 0
	v_permlane32_swap_b32_e32 v0, v45
	v_cmp_ne_u32_e64 s[0:1], 1, v12
	s_cbranch_vccnz .LBB0_1166
	global_load_dword v48, v47, s[16:17]
